# mixer queue order: sample-sequence units scheduled right after the GLA prompt chains so the phase tail is the shortest prompt DSA units
# speedup vs baseline: 1.0716x; 1.0058x over previous
; __device__ __forceinline__ int opaque_tid(int wv) { int t = wv * 64 + (int)__builtin_amdgcn_mbcnt_hi(~0u, __builtin_amdgcn_mbcnt_lo(~0u, 0u)); asm volatile("" : "+v"(t)); return t; }
; __device__ __forceinline__ void mixer_phase(int wv, const Args& A, LAS unsigned char* lds) {
;     ...
;     for (;;) {
;         __syncthreads();
;         if (opaque_tid(wv) == 0) *itemw = (int)atomicAdd(ctr, 1u);
;         __syncthreads();
;         int it = *itemw;
;         if (it >= NIT) break;
;         if (it < N_GP) { const int b = it >> 4, h = (it >> 2) & 3, sl = it & 3; gla_chain(wv, A, lds, b * 256, 256, h, sl, nullptr, A.out + O_SP + (size_t)(b * 4 + h) * 32768); continue; }
;         it -= N_GP;
;         if (it < N_DP) { dsa_unit(wv, A, lds, it & 1, 1023 - (it >> 1)); continue; }
;         it -= N_DP;
;         if (it < N_DS) { dsa_unit(wv, A, lds, 2 + (it >> 2), it & 3); continue; }
;         it -= N_DS;
;         { const int bs = it >> 4, h = (it >> 2) & 3, sl = it & 3; gla_chain(wv, A, lds, 512 + bs, 1, h, sl, A.in[5] + (size_t)(bs * 4 + h) * 32768, A.out + O_SS + (size_t)(bs * 4 + h) * 32768); }
;     }
.LBB0_857:
	s_or_b64 exec, exec, s[6:7]
	s_waitcnt lgkmcnt(0)
	s_barrier
	ds_read_b32 v0, v153
	s_movk_i32 s0, 0x8bf
	s_mov_b64 s[6:7], -1
	s_waitcnt lgkmcnt(0)
	v_cmp_lt_i32_e32 vcc, s0, v0
	v_readfirstlane_b32 s69, v0
	s_cbranch_vccnz .LBB0_852
	s_cmp_lt_u32 s69, 32
	s_cbranch_scc1 .Lq_remap_done
	s_cmpk_lt_u32 s69, 0xc0
	s_cbranch_scc1 .Lq_remap_add
	s_sub_i32 s69, s69, 0xa0
	s_branch .Lq_remap_done
.Lq_remap_add:
	s_add_i32 s69, s69, 0x800
.Lq_remap_done:
	s_cmp_gt_i32 s69, 31
	s_cbranch_scc0 .LBB0_1488
	s_cmpk_gt_u32 s69, 0x81f
	s_cbranch_scc0 .LBB0_916
	s_cmpk_gt_u32 s69, 0x83f
	s_cbranch_scc0 .LBB0_902
	s_add_i32 s0, s69, 0xfffff7c0
	s_lshr_b32 s5, s0, 4
	s_bfe_u32 s4, s69, 0x20002
	s_lshl_b32 s0, s5, 2
	s_or_b32 s12, s0, s4
	s_mov_b32 s13, s49
	s_lshl_b64 s[0:1], s[12:13], 17
	v_readlane_b32 s6, v236, 16
	v_readlane_b32 s7, v236, 17
	s_add_u32 s6, s6, s0
	v_mov_b32_e32 v94, v170
	s_addc_u32 s7, s7, s1
	s_lshl_b32 s9, s69, 6
	v_readfirstlane_b32 s1, v94
	s_ashr_i32 s0, s1, 6
	s_and_b32 s10, s9, 0xc0
	v_and_b32_e32 v91, 15, v94
	s_lshl_b32 s8, s0, 12
	s_lshl_b32 s9, s10, 2
	v_bfe_u32 v93, v94, 4, 2
	s_add_u32 s6, s6, s9
	v_lshlrev_b32_e32 v0, 2, v91
	v_readlane_b32 s14, v236, 36
	s_addc_u32 s7, s7, 0
	v_lshl_or_b32 v0, v93, 12, v0
	v_mov_b32_e32 v75, 0
	v_readlane_b32 s15, v236, 37
	v_lshl_add_u64 v[2:3], s[6:7], 0, v[0:1]
	v_cmp_ne_u32_e64 s[6:7], 1, v150
	s_andn2_b64 vcc, exec, s[14:15]
	v_mov_b32_e32 v74, v75
	s_cbranch_vccnz .LBB0_863
	s_ashr_i32 s9, s8, 31
	v_lshl_add_u64 v[4:5], s[8:9], 2, v[2:3]
	global_load_dword v74, v[4:5], off
